# speedup vs baseline: 1.0045x; 1.0045x over previous
; DI_ unsigned pk2(float lo, float hi) { typedef float f2 __attribute__((ext_vector_type(2))); typedef __bf16 b2 __attribute__((ext_vector_type(2))); f2 v = {lo, hi}; b2 b = __builtin_convertvector(v, b2); return __builtin_bit_cast(unsigned, b); }
; DI_ void ln_pass_bf16(const bf16_t* XS, bf16_t* XD, const float* g, const float* b, int gw, int NGW, int lane) {
;     ...
;     for (int row = gw; row < MTOK; row += NGW) {
;         const u32x4 a = na, c = nc;
;         if (row + NGW < MTOK) { const u32x4* rp = (const u32x4*)(XS + (size_t)(row + NGW) * D); na = rp[lane]; nc = rp[64 + lane]; }
;         float v[16]; unpack_row_bf16(a, c, v);
;         float s = 0.f;
; #pragma unroll
;         for (int e = 0; e < 16; ++e) s += v[e];
;         const float mean = wave_sum(s) * (1.f / D); float s2 = 0.f;
; #pragma unroll
;         for (int e = 0; e < 16; ++e) { v[e] -= mean; s2 += v[e] * v[e]; }
;         const float rstd = 1.f / sqrtf(wave_sum(s2) * (1.f / D) + LN_EPS);
; #pragma unroll
;         for (int e = 0; e < 16; ++e) v[e] = v[e] * rstd * gg[e] + bb[e];
;         u32x4 o0, o1; o0.x = pk2(v[0], v[1]); o0.y = pk2(v[2], v[3]); o0.z = pk2(v[4], v[5]); o0.w = pk2(v[6], v[7]); o1.x = pk2(v[8], v[9]); o1.y = pk2(v[10], v[11]); o1.z = pk2(v[12], v[13]); o1.w = pk2(v[14], v[15]);
;         u32x4* op = (u32x4*)(XD + (size_t)row * D); op[lane] = o0; op[64 + lane] = o1;
.LBB0_890:
	v_lshlrev_b32_e32 v66, 16, v40
	v_and_b32_e32 v67, 0xffff0000, v40
	v_add_f32_e32 v40, 0, v66
	v_lshlrev_b32_e32 v64, 16, v42
	v_and_b32_e32 v65, 0xffff0000, v42
	v_lshlrev_b32_e32 v42, 16, v41
	v_add_f32_e32 v40, v40, v67
	v_lshlrev_b32_e32 v58, 16, v47
	v_and_b32_e32 v59, 0xffff0000, v47
	v_lshlrev_b32_e32 v60, 16, v46
	v_and_b32_e32 v61, 0xffff0000, v46
	v_lshlrev_b32_e32 v46, 16, v45
	v_and_b32_e32 v47, 0xffff0000, v45
	v_lshlrev_b32_e32 v62, 16, v44
	v_and_b32_e32 v63, 0xffff0000, v44
	v_lshlrev_b32_e32 v44, 16, v43
	v_and_b32_e32 v45, 0xffff0000, v43
	v_and_b32_e32 v43, 0xffff0000, v41
	v_add_f32_e32 v40, v40, v42
	v_add_f32_e32 v40, v40, v43
	v_add_f32_e32 v40, v40, v64
	v_add_f32_e32 v40, v40, v65
	v_add_f32_e32 v40, v40, v44
	v_add_f32_e32 v40, v40, v45
	v_add_f32_e32 v40, v40, v62
	v_add_f32_e32 v40, v40, v63
	v_add_f32_e32 v40, v40, v46
	v_add_f32_e32 v40, v40, v47
	v_add_f32_e32 v40, v40, v60
	v_add_f32_e32 v40, v40, v61
	v_add_f32_e32 v40, v40, v58
	v_add_f32_e32 v40, v40, v59
	ds_bpermute_b32 v41, v49, v40
	s_mov_b32 s0, 0xf800000
	s_waitcnt lgkmcnt(0)
	v_add_f32_e32 v40, v40, v41
	ds_bpermute_b32 v41, v52, v40
	s_waitcnt lgkmcnt(0)
	v_add_f32_e32 v40, v40, v41
	ds_bpermute_b32 v41, v53, v40
	s_waitcnt lgkmcnt(0)
	v_add_f32_e32 v40, v40, v41
	ds_bpermute_b32 v41, v54, v40
	s_waitcnt lgkmcnt(0)
	v_add_f32_e32 v40, v40, v41
	ds_bpermute_b32 v41, v55, v40
	s_waitcnt lgkmcnt(0)
	v_add_f32_e32 v40, v40, v41
	ds_bpermute_b32 v41, v56, v40
	s_waitcnt lgkmcnt(0)
	v_add_f32_e32 v40, v40, v41
	v_mul_f32_e32 v40, 0x3a800000, v40
	v_pk_add_f32 v[66:67], v[66:67], v[40:41] op_sel_hi:[1,0] neg_lo:[0,1] neg_hi:[0,1]
	v_pk_add_f32 v[42:43], v[42:43], v[40:41] op_sel_hi:[1,0] neg_lo:[0,1] neg_hi:[0,1]
	v_pk_mul_f32 v[68:69], v[66:67], v[66:67]
	v_pk_mul_f32 v[70:71], v[42:43], v[42:43]
	v_add_f32_e32 v57, v68, v69
	v_pk_add_f32 v[64:65], v[64:65], v[40:41] op_sel_hi:[1,0] neg_lo:[0,1] neg_hi:[0,1]
	v_add_f32_e32 v57, v70, v57
	v_pk_mul_f32 v[72:73], v[64:65], v[64:65]
	v_add_f32_e32 v57, v71, v57
	v_pk_add_f32 v[44:45], v[44:45], v[40:41] op_sel_hi:[1,0] neg_lo:[0,1] neg_hi:[0,1]
	v_add_f32_e32 v57, v72, v57
	v_pk_mul_f32 v[74:75], v[44:45], v[44:45]
	v_add_f32_e32 v57, v73, v57
	v_pk_add_f32 v[62:63], v[62:63], v[40:41] op_sel_hi:[1,0] neg_lo:[0,1] neg_hi:[0,1]
	v_add_f32_e32 v57, v74, v57
	v_pk_mul_f32 v[76:77], v[62:63], v[62:63]
	v_add_f32_e32 v57, v75, v57
	v_pk_add_f32 v[46:47], v[46:47], v[40:41] op_sel_hi:[1,0] neg_lo:[0,1] neg_hi:[0,1]
	v_add_f32_e32 v57, v76, v57
	v_pk_mul_f32 v[78:79], v[46:47], v[46:47]
	v_add_f32_e32 v57, v77, v57
	v_pk_add_f32 v[60:61], v[60:61], v[40:41] op_sel_hi:[1,0] neg_lo:[0,1] neg_hi:[0,1]
	v_add_f32_e32 v57, v78, v57
	v_pk_mul_f32 v[80:81], v[60:61], v[60:61]
	v_add_f32_e32 v57, v79, v57
	v_pk_add_f32 v[40:41], v[58:59], v[40:41] op_sel_hi:[1,0] neg_lo:[0,1] neg_hi:[0,1]
	v_add_f32_e32 v57, v80, v57
	v_pk_mul_f32 v[58:59], v[40:41], v[40:41]
	v_add_f32_e32 v57, v81, v57
	v_add_f32_e32 v57, v58, v57
	v_add_f32_e32 v57, v59, v57
	ds_bpermute_b32 v58, v49, v57
	s_waitcnt lgkmcnt(0)
	v_add_f32_e32 v57, v57, v58
	ds_bpermute_b32 v58, v52, v57
	s_waitcnt lgkmcnt(0)
	v_add_f32_e32 v57, v57, v58
	ds_bpermute_b32 v58, v53, v57
	s_waitcnt lgkmcnt(0)
	v_add_f32_e32 v57, v57, v58
	ds_bpermute_b32 v58, v54, v57
	s_waitcnt lgkmcnt(0)
	v_add_f32_e32 v57, v57, v58
	ds_bpermute_b32 v58, v55, v57
	s_waitcnt lgkmcnt(0)
	v_add_f32_e32 v57, v57, v58
	ds_bpermute_b32 v58, v56, v57
	s_waitcnt lgkmcnt(0)
	v_add_f32_e32 v57, v57, v58
	v_fmamk_f32 v57, v57, 0x3a800000, v203
	v_mul_f32_e32 v58, 0x4f800000, v57
	v_cmp_gt_f32_e32 vcc, s0, v57
	s_nop 1
	v_cndmask_b32_e32 v57, v57, v58, vcc
	v_sqrt_f32_e32 v58, v57
	s_nop 0
	v_add_u32_e32 v59, -1, v58
	v_add_u32_e32 v68, 1, v58
	v_fma_f32 v69, -v59, v58, v57
	v_fma_f32 v70, -v68, v58, v57
	v_cmp_ge_f32_e64 s[0:1], 0, v69
	s_nop 1
	v_cndmask_b32_e64 v58, v58, v59, s[0:1]
	v_cmp_lt_f32_e64 s[0:1], 0, v70
	s_nop 1
	v_cndmask_b32_e64 v58, v58, v68, s[0:1]
	v_mul_f32_e32 v59, 0x37800000, v58
	v_cndmask_b32_e32 v58, v58, v59, vcc
	v_cmp_class_f32_e32 vcc, v57, v204
	s_nop 1
	v_cndmask_b32_e32 v57, v58, v57, vcc
	v_div_scale_f32 v58, s[0:1], v57, v57, 1.0
	v_rcp_f32_e32 v59, v58
	v_div_scale_f32 v68, vcc, 1.0, v57, 1.0
	v_readlane_b32 s0, v254, 24
	v_fma_f32 v69, -v58, v59, 1.0
	v_fmac_f32_e32 v59, v69, v59
	v_mul_f32_e32 v69, v68, v59
	v_fma_f32 v70, -v58, v69, v68
	v_fmac_f32_e32 v69, v70, v59
	v_fma_f32 v58, -v58, v69, v68
	v_div_fmas_f32 v58, v58, v59, v69
	v_div_fixup_f32 v58, v58, v57, 1.0
	v_pk_mul_f32 v[66:67], v[66:67], v[58:59] op_sel_hi:[1,0]
	v_pk_mul_f32 v[42:43], v[42:43], v[58:59] op_sel_hi:[1,0]
	v_pk_mul_f32 v[64:65], v[64:65], v[58:59] op_sel_hi:[1,0]
	v_pk_mul_f32 v[44:45], v[44:45], v[58:59] op_sel_hi:[1,0]
	v_pk_mul_f32 v[62:63], v[62:63], v[58:59] op_sel_hi:[1,0]
	v_pk_mul_f32 v[46:47], v[46:47], v[58:59] op_sel_hi:[1,0]
	v_pk_mul_f32 v[60:61], v[60:61], v[58:59] op_sel_hi:[1,0]
	v_pk_mul_f32 v[58:59], v[40:41], v[58:59] op_sel_hi:[1,0]
	v_pk_fma_f32 v[40:41], v[12:13], v[66:67], v[24:25]
	v_pk_fma_f32 v[42:43], v[14:15], v[42:43], v[26:27]
	v_pk_fma_f32 v[64:65], v[16:17], v[64:65], v[28:29]
	v_pk_fma_f32 v[44:45], v[18:19], v[44:45], v[30:31]
	v_pk_fma_f32 v[62:63], v[8:9], v[62:63], v[20:21]
	v_pk_fma_f32 v[46:47], v[10:11], v[46:47], v[22:23]
	v_pk_fma_f32 v[60:61], v[0:1], v[60:61], v[4:5]
	v_pk_fma_f32 v[58:59], v[2:3], v[58:59], v[6:7]
	v_cvt_pk_bf16_f32 v40, v40, v41
	v_cvt_pk_bf16_f32 v41, v42, v43
	v_cvt_pk_bf16_f32 v42, v64, v65
	v_cvt_pk_bf16_f32 v43, v44, v45
	v_cvt_pk_bf16_f32 v44, v62, v63
	v_cvt_pk_bf16_f32 v45, v46, v47
	v_cvt_pk_bf16_f32 v46, v60, v61
	v_cvt_pk_bf16_f32 v47, v58, v59
	v_lshl_add_u64 v[58:59], v[50:51], 0, s[10:11]
	global_store_dwordx4 v[58:59], v[40:43], off offset:-1024
	global_store_dwordx4 v[58:59], v[44:47], off
	v_readlane_b32 s1, v254, 25
	s_add_i32 vcc_lo, s6, s94
	s_cmpk_gt_i32 vcc_lo, 0x7fff
	s_cbranch_scc1 .Lmy_ln1_w2
	s_waitcnt vmcnt(4)
	s_branch .Lmy_ln1_wd
; DI_ void ln_pass_bf16(const bf16_t* XS, bf16_t* XD, const float* g, const float* b, int gw, int NGW, int lane) {
;     ...
;     for (int row = gw; row < MTOK; row += NGW) {
;         const u32x4 a = na, c = nc;
;         if (row + NGW < MTOK) { const u32x4* rp = (const u32x4*)(XS + (size_t)(row + NGW) * D); na = rp[lane]; nc = rp[64 + lane]; }
.Lmy_ln1_w2:
	s_waitcnt vmcnt(2)
.Lmy_ln1_wd:
	s_bitcmp1_b32 s6, 11
	s_cbranch_scc0 .Lmy_ln1_mvM
	v_mov_b64_e32 v[40:41], v[36:37]
	v_mov_b64_e32 v[42:43], v[38:39]
	v_mov_b64_e32 v[44:45], v[32:33]
	v_mov_b64_e32 v[46:47], v[34:35]
	s_branch .Lmy_ln1_mvd
.Lmy_ln1_mvM:
	v_mov_b64_e32 v[40:41], v[206:207]
	v_mov_b64_e32 v[42:43], v[208:209]
	v_mov_b64_e32 v[44:45], v[210:211]
	v_mov_b64_e32 v[46:47], v[212:213]
.Lmy_ln1_mvd:
	v_lshl_add_u64 v[50:51], v[50:51], 0, s[0:1]
	s_andn2_b64 vcc, exec, s[38:39]
	s_cbranch_vccz .LBB0_893
.LBB0_891:
	s_add_i32 s6, s6, s94
	s_cmpk_gt_i32 s6, 0x7fff
	s_cselect_b64 s[38:39], -1, 0
	s_add_i32 s0, s6, s94
	s_cmpk_gt_i32 s0, 0x7fff
	s_cbranch_scc1 .LBB0_890
	v_readlane_b32 s0, v254, 24
	v_readlane_b32 s1, v254, 25
	v_lshl_add_u64 v[214:215], v[50:51], 0, s[18:19]
	s_nop 1
	v_lshl_add_u64 v[214:215], v[214:215], 0, s[0:1]
	s_bitcmp1_b32 s6, 11
	s_cbranch_scc0 .Lmy_ln1_ldN
	global_load_dwordx4 v[206:209], v[214:215], off offset:-1024
	global_load_dwordx4 v[210:213], v[214:215], off
	s_branch .LBB0_890
.Lmy_ln1_ldN:
	global_load_dwordx4 v[36:39], v[214:215], off offset:-1024
	s_nop 0
	global_load_dwordx4 v[32:35], v[214:215], off
	s_branch .LBB0_890
.Lmy_ln1_pro:
	s_add_i32 s0, s6, s94
	s_cmpk_gt_i32 s0, 0x7fff
	s_cbranch_scc1 .LBB0_891
	v_lshl_add_u64 v[214:215], v[50:51], 0, s[18:19]
	global_load_dwordx4 v[36:39], v[214:215], off offset:-1024
	global_load_dwordx4 v[32:35], v[214:215], off
	s_branch .LBB0_891
